# lora GEMM: skip structurally-zero K blocks of the packed block-diagonal up-projection (one k-step pair per tile); XCD barrier also after phase 0
# speedup vs baseline: 1.0149x; 1.0149x over previous
.LBB0_395:
	s_cmp_lg_u32 s21, 0
	s_cbranch_scc0 .Lsx0_a
	s_add_i32 s24, s21, -16
	s_and_b64 s[2:3], s[12:13], exec
	s_cselect_b32 s2, s24, s19
	ds_read_b64 v[236:237], v190 offset:4096
	v_lshl_add_u32 v194, s2, 6, v183
	v_lshl_add_u64 v[238:239], v[194:195], 1, s[78:79]
.Lsx0_a:
	v_add_u32_e32 v192, v144, v145
	v_add_u32_e32 v199, v150, v145
	s_and_saveexec_b64 s[2:3], s[54:55]
	s_cbranch_execz .Lsx0_c
	s_cmp_lg_u32 s21, 0
	s_cbranch_scc0 .Lsx0_c
	s_waitcnt lgkmcnt(0)
	v_cvt_pk_bf16_f32 v240, v236, v237
	global_store_dword v[238:239], v240, off
.Lsx0_c:
	s_or_b64 exec, exec, s[2:3]
	v_mov_b32_e32 v22, 0
	v_mov_b32_e32 v23, 0
	v_mov_b32_e32 v24, 0
	v_mov_b32_e32 v25, 0
	s_and_saveexec_b64 s[2:3], s[56:57]
	s_cbranch_execz .LBB0_403
	ds_read_b128 v[48:51], v174
	ds_read_b128 v[60:63], v192 offset:49152
	ds_read_b128 v[52:55], v174 offset:64
	ds_read_b128 v[64:67], v192 offset:49216
	ds_read_b128 v[56:59], v175
	ds_read_b128 v[68:71], v199
	ds_read_b128 v[72:75], v192 offset:58368
	ds_read_b128 v[76:79], v192 offset:58432
	s_waitcnt lgkmcnt(6)
	v_mfma_f32_16x16x32_bf16 v[30:33], v[48:51], v[60:63], 0
	s_waitcnt lgkmcnt(4)
	v_mfma_f32_16x16x32_bf16 v[30:33], v[52:55], v[64:67], v[30:33]
	s_waitcnt lgkmcnt(2)
	v_mfma_f32_16x16x32_bf16 v[30:33], v[56:59], v[68:71], v[30:33]
	s_waitcnt lgkmcnt(1)
	v_mfma_f32_16x16x32_bf16 v[22:25], v[48:51], v[72:75], 0
	s_waitcnt lgkmcnt(0)
	v_mfma_f32_16x16x32_bf16 v[22:25], v[52:55], v[76:79], v[22:25]
	s_cmp_lg_u32 s21, 0
	s_cbranch_scc0 .Lsx0_d
	v_cvt_pk_bf16_f32 v240, v236, v237
	global_store_dword v[238:239], v240, off

.LBB0_426:
	s_add_i32 s24, s19, -16
	s_and_b64 s[2:3], s[12:13], exec
	s_waitcnt lgkmcnt(0)
	s_barrier
	s_cselect_b32 s2, s21, s24
	s_cmpk_lt_u32 s20, 0x7f
	ds_read_b64 v[236:237], v190
	v_lshl_add_u32 v194, s2, 6, v183
	s_cselect_b64 s[2:3], -1, 0
	v_lshl_add_u64 v[238:239], v[194:195], 1, s[78:79]
	s_and_b64 s[68:69], s[54:55], s[2:3]
	s_and_saveexec_b64 s[74:75], s[54:55]
	s_cbranch_execz .Lsx1_c
	s_waitcnt lgkmcnt(0)
	v_cvt_pk_bf16_f32 v240, v236, v237
	global_store_dword v[238:239], v240, off
.Lsx1_c:
	s_or_b64 exec, exec, s[74:75]
	v_mov_b32_e32 v22, 0
	v_mov_b32_e32 v23, 0
	v_mov_b32_e32 v24, 0
	v_mov_b32_e32 v25, 0
	s_and_saveexec_b64 s[74:75], s[56:57]
	s_cbranch_execz .LBB0_432
	ds_read_b128 v[48:51], v174
	ds_read_b128 v[60:63], v192 offset:51456
	ds_read_b128 v[52:55], v174 offset:64
	ds_read_b128 v[64:67], v192 offset:51520
	ds_read_b128 v[56:59], v175 offset:5120
	ds_read_b128 v[68:71], v199
	ds_read_b128 v[72:75], v192 offset:60672
	ds_read_b128 v[76:79], v192 offset:60736
	s_waitcnt lgkmcnt(6)
	v_mfma_f32_16x16x32_bf16 v[30:33], v[48:51], v[60:63], 0
	s_waitcnt lgkmcnt(4)
	v_mfma_f32_16x16x32_bf16 v[30:33], v[52:55], v[64:67], v[30:33]
	s_waitcnt lgkmcnt(2)
	v_mfma_f32_16x16x32_bf16 v[30:33], v[56:59], v[68:71], v[30:33]
	s_waitcnt lgkmcnt(1)
	v_mfma_f32_16x16x32_bf16 v[22:25], v[48:51], v[72:75], 0
	s_waitcnt lgkmcnt(0)
	v_mfma_f32_16x16x32_bf16 v[22:25], v[52:55], v[76:79], v[22:25]
	v_cvt_pk_bf16_f32 v240, v236, v237
	global_store_dword v[238:239], v240, off
	s_nop 3
	ds_write_b128 v176, v[30:33]

.LBB0_463:
	s_ashr_i32 s0, s7, 3
	s_waitcnt lgkmcnt(0)
	s_add_u32 s56, s38, 0x2092b400
	s_addc_u32 s57, s39, 0
	s_mov_b32 s1, 0x7fffe0
	s_add_u32 s58, s38, 0x1680000
	v_and_or_b32 v0, v173, s1, v177
	s_addc_u32 s59, s39, 0
	v_or3_b32 v0, v0, v176, v175
	s_add_i32 s0, s6, s0
	v_lshl_add_u32 v150, v0, 9, v160
	v_and_or_b32 v0, v178, s1, v182
	s_ashr_i32 s1, s0, 31
	s_lshr_b32 s1, s1, 25
	s_add_i32 s1, s0, s1
	s_ashr_i32 s6, s1, 7
	s_and_b32 s1, s1, 0xff80
	s_sub_i32 s0, s0, s1
	s_bfe_i32 s1, s0, 0x80000
	s_bfe_u32 s1, s1, 0x3000c
	s_add_i32 s1, s0, s1
	s_lshl_b32 s9, s6, 3
	s_bfe_i32 s6, s1, 0x80000
	s_and_b32 s1, s1, 0xf8
	s_sub_i32 s0, s0, s1
	s_sext_i32_i16 s6, s6
	s_sext_i32_i8 s0, s0
	s_ashr_i32 s7, s54, 6
	s_lshr_b32 s6, s6, 3
	s_add_i32 s0, s9, s0
	s_ashr_i32 s1, s0, 31
	s_bfe_i64 s[12:13], s[6:7], 0x100000
	s_ashr_i32 s8, s54, 8
	s_lshl_b32 s60, s7, 10
	s_lshl_b64 s[10:11], s[0:1], 17
	s_lshl_b64 s[12:13], s[12:13], 17
	s_add_u32 s12, s58, s12
	s_addc_u32 s13, s59, s13
	s_lshr_b32 s98, s6, 3
	s_lshl_b32 s98, s98, 8
	s_add_u32 s12, s12, s98
	s_addc_u32 s13, s13, 0
	s_add_i32 s61, s60, 0
	s_add_i32 m0, s61, 0x10000
	v_or3_b32 v0, v0, v181, v180
	global_load_lds_dwordx4 v150, s[12:13]
	s_add_i32 m0, s61, 0x12000
	v_lshl_add_u32 v154, v0, 9, v161
	s_add_u32 s34, s56, s10
	v_lshl_add_u32 v8, v173, 9, v160
	global_load_lds_dwordx4 v154, s[12:13]
	s_addc_u32 s35, s57, s11
	s_add_u32 s34, s34, s98
	s_addc_u32 s35, s35, 0
	s_mov_b32 m0, s61
	s_add_i32 s62, s61, 0x2000
	v_lshl_add_u32 v152, v178, 9, v161
	global_load_lds_dwordx4 v8, s[34:35]
	s_mov_b32 m0, s62
	s_add_u32 s10, s12, 0x10000
	global_load_lds_dwordx4 v152, s[34:35]
	s_addc_u32 s11, s13, 0
	s_add_i32 m0, s61, 0x14000
	v_mov_b32_e32 v151, v195
	global_load_lds_dwordx4 v150, s[10:11]
	s_add_i32 m0, s61, 0x16000
	v_mov_b32_e32 v155, v195
	global_load_lds_dwordx4 v154, s[10:11]
	s_add_u32 s10, s34, 0x10000
	s_addc_u32 s11, s35, 0
	s_add_i32 s63, s61, 0x4000
	s_mov_b32 m0, s63
	s_add_i32 s64, s61, 0x6000
	global_load_lds_dwordx4 v8, s[10:11]
	s_mov_b32 m0, s64
	v_mov_b32_e32 v9, v195
	global_load_lds_dwordx4 v152, s[10:11]
	v_mov_b32_e32 v153, v195
	v_lshl_add_u64 v[6:7], s[12:13], 0, v[150:151]
	v_lshl_add_u64 v[4:5], s[12:13], 0, v[154:155]
	v_lshl_add_u64 v[2:3], s[34:35], 0, v[8:9]
	s_cmp_lg_u32 s8, 1
	v_lshl_add_u64 v[0:1], s[34:35], 0, v[152:153]
	s_cbranch_scc1 .LBB0_465
	s_barrier

.LBB0_472:
	v_mov_b64_e32 v[0:1], 0x400
	s_ashr_i32 s7, s6, 31
	v_cmp_lt_i64_e32 vcc, s[2:3], v[0:1]
	s_lshl_b64 s[2:3], s[6:7], 17
	s_add_u32 s8, s56, s2
	s_addc_u32 s9, s57, s3
	s_lshr_b32 s98, s4, 3
	s_lshl_b32 s98, s98, 8
	s_add_u32 s8, s8, s98
	s_addc_u32 s9, s9, 0
	s_and_b64 s[2:3], vcc, exec
	s_cselect_b32 s7, s9, s35
	s_cselect_b32 s19, s8, s34
	s_ashr_i32 s5, s4, 31
	s_lshl_b64 s[2:3], s[4:5], 17
	s_add_u32 s10, s58, s2
	s_addc_u32 s11, s59, s3
	s_add_u32 s10, s10, s98
	s_addc_u32 s11, s11, 0
	s_and_b64 s[2:3], vcc, exec
	v_mov_b32_e32 v0, 0
	s_cselect_b32 s5, s11, s13
	s_cselect_b32 s20, s10, s12
	s_mov_b32 s21, 0
	s_mov_b64 s[42:43], 0
	s_mov_b64 s[2:3], -1
	v_mov_b32_e32 v1, v0
	v_mov_b32_e32 v2, v0
	v_mov_b32_e32 v3, v0
	v_mov_b32_e32 v4, v0
	v_mov_b32_e32 v5, v0
	v_mov_b32_e32 v6, v0
	v_mov_b32_e32 v7, v0
	v_mov_b32_e32 v22, v0
	v_mov_b32_e32 v23, v0
	v_mov_b32_e32 v24, v0
	v_mov_b32_e32 v25, v0
	v_mov_b32_e32 v26, v0
	v_mov_b32_e32 v27, v0
	v_mov_b32_e32 v28, v0
	v_mov_b32_e32 v29, v0
	v_mov_b32_e32 v38, v0
	v_mov_b32_e32 v39, v0
	v_mov_b32_e32 v40, v0
	v_mov_b32_e32 v41, v0
	v_mov_b32_e32 v42, v0
	v_mov_b32_e32 v43, v0
	v_mov_b32_e32 v44, v0
	v_mov_b32_e32 v45, v0
	v_mov_b32_e32 v70, v0
	v_mov_b32_e32 v71, v0
	v_mov_b32_e32 v72, v0
	v_mov_b32_e32 v73, v0
	v_mov_b32_e32 v74, v0
	v_mov_b32_e32 v75, v0
	v_mov_b32_e32 v76, v0
	v_mov_b32_e32 v77, v0
	v_mov_b32_e32 v14, v0
	v_mov_b32_e32 v15, v0
	v_mov_b32_e32 v16, v0
	v_mov_b32_e32 v17, v0
	v_mov_b32_e32 v18, v0
	v_mov_b32_e32 v19, v0
	v_mov_b32_e32 v20, v0
	v_mov_b32_e32 v21, v0
	v_mov_b32_e32 v30, v0
	v_mov_b32_e32 v31, v0
	v_mov_b32_e32 v32, v0
	v_mov_b32_e32 v33, v0
	v_mov_b32_e32 v34, v0
	v_mov_b32_e32 v35, v0
	v_mov_b32_e32 v36, v0
	v_mov_b32_e32 v37, v0
	v_mov_b32_e32 v54, v0
	v_mov_b32_e32 v55, v0
	v_mov_b32_e32 v56, v0
	v_mov_b32_e32 v57, v0
	v_mov_b32_e32 v58, v0
	v_mov_b32_e32 v59, v0
	v_mov_b32_e32 v60, v0
	v_mov_b32_e32 v61, v0
	v_mov_b32_e32 v78, v0
	v_mov_b32_e32 v79, v0
	v_mov_b32_e32 v80, v0
	v_mov_b32_e32 v81, v0
	v_mov_b32_e32 v82, v0
	v_mov_b32_e32 v83, v0
	v_mov_b32_e32 v84, v0
	v_mov_b32_e32 v85, v0
	v_mov_b32_e32 v86, v0
	v_mov_b32_e32 v87, v0
	v_mov_b32_e32 v88, v0
	v_mov_b32_e32 v89, v0
	v_mov_b32_e32 v90, v0
	v_mov_b32_e32 v91, v0
	v_mov_b32_e32 v92, v0
	v_mov_b32_e32 v93, v0
	v_mov_b32_e32 v102, v0
	v_mov_b32_e32 v103, v0
	v_mov_b32_e32 v104, v0
	v_mov_b32_e32 v105, v0
	v_mov_b32_e32 v106, v0
	v_mov_b32_e32 v107, v0
	v_mov_b32_e32 v108, v0
	v_mov_b32_e32 v109, v0
	v_mov_b32_e32 v118, v0
	v_mov_b32_e32 v119, v0
	v_mov_b32_e32 v120, v0
	v_mov_b32_e32 v121, v0
	v_mov_b32_e32 v122, v0
	v_mov_b32_e32 v123, v0
	v_mov_b32_e32 v124, v0
	v_mov_b32_e32 v125, v0
	v_mov_b32_e32 v134, v0
	v_mov_b32_e32 v135, v0
	v_mov_b32_e32 v136, v0
	v_mov_b32_e32 v137, v0
	v_mov_b32_e32 v138, v0
	v_mov_b32_e32 v139, v0
	v_mov_b32_e32 v140, v0
	v_mov_b32_e32 v141, v0
	v_mov_b32_e32 v94, v0
	v_mov_b32_e32 v95, v0
	v_mov_b32_e32 v96, v0
	v_mov_b32_e32 v97, v0
	v_mov_b32_e32 v98, v0
	v_mov_b32_e32 v99, v0
	v_mov_b32_e32 v100, v0
	v_mov_b32_e32 v101, v0
	v_mov_b32_e32 v110, v0
	v_mov_b32_e32 v111, v0
	v_mov_b32_e32 v112, v0
	v_mov_b32_e32 v113, v0
	v_mov_b32_e32 v114, v0
	v_mov_b32_e32 v115, v0
	v_mov_b32_e32 v116, v0
	v_mov_b32_e32 v117, v0
	v_mov_b32_e32 v126, v0
	v_mov_b32_e32 v127, v0
	v_mov_b32_e32 v128, v0
	v_mov_b32_e32 v129, v0
	v_mov_b32_e32 v130, v0
	v_mov_b32_e32 v131, v0
	v_mov_b32_e32 v132, v0
	v_mov_b32_e32 v133, v0
	v_mov_b32_e32 v142, v0
	v_mov_b32_e32 v143, v0
	v_mov_b32_e32 v144, v0
	v_mov_b32_e32 v145, v0
	v_mov_b32_e32 v146, v0
	v_mov_b32_e32 v147, v0
	v_mov_b32_e32 v148, v0
	v_mov_b32_e32 v149, v0

.LBB0_1009:
	v_readlane_b32 s0, v254, 33
	v_readlane_b32 s1, v254, 34
	s_and_b64 vcc, exec, s[0:1]
	s_nop 0
	s_waitcnt vmcnt(0)
	s_waitcnt lgkmcnt(0)
	s_barrier
	s_mov_b64 s[0:1], exec
	v_readlane_b32 s2, v252, 2
	v_readlane_b32 s3, v252, 3
	s_and_b64 s[2:3], s[0:1], s[2:3]
	s_mov_b64 exec, s[2:3]
	s_cbranch_execz .LBB0_1063
	s_add_i32 s8, 0, 0x20000
	v_mov_b32_e32 v0, s8
	s_waitcnt vmcnt(0) expcnt(0) lgkmcnt(0)
	ds_read_b32 v2, v0
	v_readlane_b32 s2, v254, 5
	s_waitcnt lgkmcnt(0)
	v_cmp_ne_u32_e32 vcc, 0, v2
	v_mov_b32_e32 v0, s2
	ds_read_b32 v0, v0
	s_cbranch_vccnz .LBB0_1027
	v_readlane_b32 s4, v252, 0
	v_readlane_b32 s5, v252, 1
	s_load_dwordx2 s[2:3], s[4:5], 0x4
	s_mov_b32 s10, 1
	s_waitcnt lgkmcnt(0)
	s_mul_i32 s9, s2, s71
	s_mul_i32 s9, s9, s3
	s_branch .LBB0_1014
